# v70: barrier polling cadence - s_sleep 3 instead of s_sleep 1 between polls of the top counter (fewer polls on the hot line)
# baseline (speedup 1.0000x reference)
; __device__ __forceinline__ unsigned xb_ld(unsigned* p)              { return __hip_atomic_load(p, __ATOMIC_RELAXED, __HIP_MEMORY_SCOPE_AGENT); }
; __device__ __forceinline__ unsigned xb_add(unsigned* p, unsigned v) { return __hip_atomic_fetch_add(p, v, __ATOMIC_RELAXED, __HIP_MEMORY_SCOPE_AGENT); }
; #define XB_SPIN(cond, bar) do { unsigned _sp = 0; while (cond) { __builtin_amdgcn_s_sleep(1); \
;     if ((++_sp & 255u) == 0u) { if (xb_ld(&(bar)[XB_TMO])) break; if (_sp > XB_SPIN_CAP) { atomicAdd(&(bar)[XB_TMO], 1u); break; } } } } while (0)
; __device__ __forceinline__ void xcd_barrier(const XcdBarrier& b) {
;     ...
;             const unsigned og = xb_add(&bar[XB_TOP], 1u);
;             const unsigned tg = og / nx;
;             if (og + 1u == (tg + 1u) * nx) xb_add(&bar[XB_TOPGEN], 1u);
;             else XB_SPIN(xb_ld(&bar[XB_TOPGEN]) == tg, bar);
;             __builtin_amdgcn_fence(__ATOMIC_ACQUIRE, "agent");
;             xb_add(&bar[XB_XGEN(b.x)], 1u);
;             asm volatile("s_waitcnt vmcnt(0)" ::: "memory");
;         } else {
;             XB_SPIN(xb_ld(&bar[XB_XGEN(b.x)]) == gen, bar);
.Lfb0_spin:
	global_load_dword v5, v4, s[4:5] sc1
	s_waitcnt vmcnt(0)
	v_cmp_ge_u32_e32 vcc, v5, v3
	s_cbranch_vccnz .Lfb0_done
	s_sleep 3
	s_add_u32 s3, s3, 1
	s_cmp_lt_u32 s3, 0x200000
	s_cbranch_scc1 .Lfb0_spin

; __device__ __forceinline__ unsigned xb_ld(unsigned* p)              { return __hip_atomic_load(p, __ATOMIC_RELAXED, __HIP_MEMORY_SCOPE_AGENT); }
; __device__ __forceinline__ unsigned xb_add(unsigned* p, unsigned v) { return __hip_atomic_fetch_add(p, v, __ATOMIC_RELAXED, __HIP_MEMORY_SCOPE_AGENT); }
; #define XB_SPIN(cond, bar) do { unsigned _sp = 0; while (cond) { __builtin_amdgcn_s_sleep(1); \
;     if ((++_sp & 255u) == 0u) { if (xb_ld(&(bar)[XB_TMO])) break; if (_sp > XB_SPIN_CAP) { atomicAdd(&(bar)[XB_TMO], 1u); break; } } } } while (0)
; __device__ __forceinline__ void xcd_barrier(const XcdBarrier& b) {
;     ...
;             const unsigned og = xb_add(&bar[XB_TOP], 1u);
;             const unsigned tg = og / nx;
;             if (og + 1u == (tg + 1u) * nx) xb_add(&bar[XB_TOPGEN], 1u);
;             else XB_SPIN(xb_ld(&bar[XB_TOPGEN]) == tg, bar);
;             __builtin_amdgcn_fence(__ATOMIC_ACQUIRE, "agent");
;             xb_add(&bar[XB_XGEN(b.x)], 1u);
;             asm volatile("s_waitcnt vmcnt(0)" ::: "memory");
;         } else {
;             XB_SPIN(xb_ld(&bar[XB_XGEN(b.x)]) == gen, bar);
.Lfb2_spin:
	global_load_dword v5, v4, s[4:5] sc1
	s_waitcnt vmcnt(0)
	v_cmp_ge_u32_e32 vcc, v5, v3
	s_cbranch_vccnz .Lfb2_done
	s_sleep 3
	s_add_u32 s6, s6, 1
	s_cmp_lt_u32 s6, 0x200000
	s_cbranch_scc1 .Lfb2_spin

; __device__ __forceinline__ unsigned xb_ld(unsigned* p)              { return __hip_atomic_load(p, __ATOMIC_RELAXED, __HIP_MEMORY_SCOPE_AGENT); }
; __device__ __forceinline__ unsigned xb_add(unsigned* p, unsigned v) { return __hip_atomic_fetch_add(p, v, __ATOMIC_RELAXED, __HIP_MEMORY_SCOPE_AGENT); }
; #define XB_SPIN(cond, bar) do { unsigned _sp = 0; while (cond) { __builtin_amdgcn_s_sleep(1); \
;     if ((++_sp & 255u) == 0u) { if (xb_ld(&(bar)[XB_TMO])) break; if (_sp > XB_SPIN_CAP) { atomicAdd(&(bar)[XB_TMO], 1u); break; } } } } while (0)
; __device__ __forceinline__ void xcd_barrier(const XcdBarrier& b) {
;     ...
;             const unsigned og = xb_add(&bar[XB_TOP], 1u);
;             const unsigned tg = og / nx;
;             if (og + 1u == (tg + 1u) * nx) xb_add(&bar[XB_TOPGEN], 1u);
;             else XB_SPIN(xb_ld(&bar[XB_TOPGEN]) == tg, bar);
;             __builtin_amdgcn_fence(__ATOMIC_ACQUIRE, "agent");
;             xb_add(&bar[XB_XGEN(b.x)], 1u);
;             asm volatile("s_waitcnt vmcnt(0)" ::: "memory");
;         } else {
;             XB_SPIN(xb_ld(&bar[XB_XGEN(b.x)]) == gen, bar);
.Lfb6_spin:
	global_load_dword v5, v4, s[8:9] sc1
	s_waitcnt vmcnt(0)
	v_cmp_ge_u32_e32 vcc, v5, v3
	s_cbranch_vccnz .Lfb6_done
	s_sleep 3
	s_add_u32 s3, s3, 1
	s_cmp_lt_u32 s3, 0x200000
	s_cbranch_scc1 .Lfb6_spin

; __device__ __forceinline__ unsigned xb_ld(unsigned* p)              { return __hip_atomic_load(p, __ATOMIC_RELAXED, __HIP_MEMORY_SCOPE_AGENT); }
; __device__ __forceinline__ unsigned xb_add(unsigned* p, unsigned v) { return __hip_atomic_fetch_add(p, v, __ATOMIC_RELAXED, __HIP_MEMORY_SCOPE_AGENT); }
; #define XB_SPIN(cond, bar) do { unsigned _sp = 0; while (cond) { __builtin_amdgcn_s_sleep(1); \
;     if ((++_sp & 255u) == 0u) { if (xb_ld(&(bar)[XB_TMO])) break; if (_sp > XB_SPIN_CAP) { atomicAdd(&(bar)[XB_TMO], 1u); break; } } } } while (0)
; __device__ __forceinline__ void xcd_barrier(const XcdBarrier& b) {
;     ...
;             const unsigned og = xb_add(&bar[XB_TOP], 1u);
;             const unsigned tg = og / nx;
;             if (og + 1u == (tg + 1u) * nx) xb_add(&bar[XB_TOPGEN], 1u);
;             else XB_SPIN(xb_ld(&bar[XB_TOPGEN]) == tg, bar);
;             __builtin_amdgcn_fence(__ATOMIC_ACQUIRE, "agent");
;             xb_add(&bar[XB_XGEN(b.x)], 1u);
;             asm volatile("s_waitcnt vmcnt(0)" ::: "memory");
;         } else {
;             XB_SPIN(xb_ld(&bar[XB_XGEN(b.x)]) == gen, bar);
.Lfb8_spin:
	global_load_dword v4, v1, s[6:7] sc1
	s_waitcnt vmcnt(0)
	v_cmp_ge_u32_e32 vcc, v4, v3
	s_cbranch_vccnz .Lfb8_done
	s_sleep 3
	s_add_u32 s8, s8, 1
	s_cmp_lt_u32 s8, 0x200000
	s_cbranch_scc1 .Lfb8_spin

; __device__ __forceinline__ unsigned xb_ld(unsigned* p)              { return __hip_atomic_load(p, __ATOMIC_RELAXED, __HIP_MEMORY_SCOPE_AGENT); }
; __device__ __forceinline__ unsigned xb_add(unsigned* p, unsigned v) { return __hip_atomic_fetch_add(p, v, __ATOMIC_RELAXED, __HIP_MEMORY_SCOPE_AGENT); }
; #define XB_SPIN(cond, bar) do { unsigned _sp = 0; while (cond) { __builtin_amdgcn_s_sleep(1); \
;     if ((++_sp & 255u) == 0u) { if (xb_ld(&(bar)[XB_TMO])) break; if (_sp > XB_SPIN_CAP) { atomicAdd(&(bar)[XB_TMO], 1u); break; } } } } while (0)
; __device__ __forceinline__ void xcd_barrier(const XcdBarrier& b) {
;     ...
;             const unsigned og = xb_add(&bar[XB_TOP], 1u);
;             const unsigned tg = og / nx;
;             if (og + 1u == (tg + 1u) * nx) xb_add(&bar[XB_TOPGEN], 1u);
;             else XB_SPIN(xb_ld(&bar[XB_TOPGEN]) == tg, bar);
;             __builtin_amdgcn_fence(__ATOMIC_ACQUIRE, "agent");
;             xb_add(&bar[XB_XGEN(b.x)], 1u);
;             asm volatile("s_waitcnt vmcnt(0)" ::: "memory");
;         } else {
;             XB_SPIN(xb_ld(&bar[XB_XGEN(b.x)]) == gen, bar);
.Lfb9_spin:
	global_load_dword v3, v2, s[6:7] sc1
	s_waitcnt vmcnt(0)
	v_cmp_ge_u32_e32 vcc, v3, v1
	s_cbranch_vccnz .Lfb9_done
	s_sleep 3
	s_add_u32 s8, s8, 1
	s_cmp_lt_u32 s8, 0x200000
	s_cbranch_scc1 .Lfb9_spin
